# Down/Out residual epilogues: dropped the 14 lgkmcnt(0) waits that only guarded the removed ds_bpermute results (no LDS/SMEM op left in those epilogues)
# baseline (speedup 1.0000x reference)
; __device__ __forceinline__ float lane_xor(float v, int lane, int o) { return __builtin_bit_cast(float, __builtin_amdgcn_ds_bpermute((lane ^ o) << 2, __builtin_bit_cast(int, v))); }
; __device__ __forceinline__ unsigned cvt_pk_bf16(float lo, float hi) { unsigned r; asm volatile("v_cvt_pk_bf16_f32 %0, %1, %2" : "=v"(r) : "v"(lo), "v"(hi)); return r; }
;     __device__ __forceinline__ void operator()(const f32x4 (&acc)[2][2][4][2], const Unit& u, int wr, int wc, int fr_in, int fq_in) const {
;     ...
;             for (int m = 0; m < 4; ++m) {
;                 const int row = row0 + ai * HALF + m * 16;
;                 bf16_t* xp = XN + (size_t)row * DM + col0;
;                 float sq = 0.f;
; #pragma unroll
;                 for (int bj = 0; bj < 2; ++bj) {
;                     const f32x4 a = hv[m][bj][0] + acc[ai][bj][m][0] * alpha, b = hv[m][bj][1] + acc[ai][bj][m][1] * alpha;
;                     *(f32x4*)(hp[m] + bj * HALF) = a; *(f32x4*)(hp[m] + bj * HALF + 4) = b;
;                     sq += (a[0] * a[0] + a[1] * a[1]) + (a[2] * a[2] + a[3] * a[3]) + (b[0] * b[0] + b[1] * b[1]) + (b[2] * b[2] + b[3] * b[3]);
;                     const f32x4 xa = a * gv[bj][0], xb = b * gv[bj][1];
;                     u32x4 w; w.x = cvt_pk_bf16(xa[0], xa[1]); w.y = cvt_pk_bf16(xa[2], xa[3]); w.z = cvt_pk_bf16(xb[0], xb[1]); w.w = cvt_pk_bf16(xb[2], xb[3]);
;                     *(u32x4*)(xp + bj * HALF) = w;
;                 }
;                 sq += lane_xor(sq, lane, 16); sq += lane_xor(sq, lane, 32);
;                 if (fq == 0) atomicAdd(SSout + row, sq);
.LBB0_309:
	s_or_b64 exec, exec, s[4:5]
	v_pk_fma_f32 v[128:129], v[128:129], 0.5, v[200:201] op_sel_hi:[1,0,1]
	v_pk_fma_f32 v[126:127], v[126:127], 0.5, v[198:199] op_sel_hi:[1,0,1]
	v_mul_f32_e32 v134, v129, v129
	v_mul_f32_e32 v0, v127, v127
	v_pk_fma_f32 v[122:123], v[122:123], 0.5, v[194:195] op_sel_hi:[1,0,1]
	v_fmac_f32_e32 v0, v126, v126
	v_fmac_f32_e32 v134, v128, v128
	v_add_f32_e32 v0, v0, v134
	v_mul_f32_e32 v134, v123, v123
	v_ashrrev_i32_e32 v245, 31, v244
	v_pk_fma_f32 v[124:125], v[124:125], 0.5, v[196:197] op_sel_hi:[1,0,1]
	v_fmac_f32_e32 v134, v122, v122
	v_lshlrev_b64 v[132:133], 11, v[244:245]
	v_add_f32_e32 v0, v134, v0
	v_mul_f32_e32 v134, v125, v125
	v_lshl_add_u64 v[130:131], v[232:233], 2, v[248:249]
	v_lshl_add_u64 v[132:133], s[58:59], 0, v[132:133]
	v_fmac_f32_e32 v134, v124, v124
	v_lshl_add_u64 v[132:133], v[232:233], 1, v[132:133]
	flat_store_dwordx4 v[130:131], v[126:129]
	flat_store_dwordx4 v[130:131], v[122:125] offset:16
	v_add_f32_e32 v0, v134, v0
	v_pk_mul_f32 v[128:129], v[80:81], v[128:129]
	v_pk_mul_f32 v[126:127], v[78:79], v[126:127]
	v_pk_mul_f32 v[134:135], v[76:77], v[124:125]
	v_pk_mul_f32 v[124:125], v[74:75], v[122:123]
	v_cvt_pk_bf16_f32 v122, v126, v127
	v_cvt_pk_bf16_f32 v123, v128, v129
	v_pk_fma_f32 v[120:121], v[120:121], 0.5, v[172:173] op_sel_hi:[1,0,1]
	v_pk_fma_f32 v[118:119], v[118:119], 0.5, v[170:171] op_sel_hi:[1,0,1]
	v_cvt_pk_bf16_f32 v124, v124, v125
	v_cvt_pk_bf16_f32 v125, v134, v135
	flat_store_dwordx4 v[132:133], v[122:125]
	v_pk_fma_f32 v[114:115], v[114:115], 0.5, v[162:163] op_sel_hi:[1,0,1]
	v_pk_fma_f32 v[116:117], v[116:117], 0.5, v[164:165] op_sel_hi:[1,0,1]
	v_mul_f32_e32 v122, v119, v119
	v_mul_f32_e32 v123, v121, v121
	v_fmac_f32_e32 v122, v118, v118
	v_fmac_f32_e32 v123, v120, v120
	v_add_f32_e32 v122, v122, v123
	v_mul_f32_e32 v123, v115, v115
	v_fmac_f32_e32 v123, v114, v114
	v_add_f32_e32 v122, v123, v122
	v_mul_f32_e32 v123, v117, v117
	v_fmac_f32_e32 v123, v116, v116
	v_add_f32_e32 v122, v123, v122
	v_add_f32_e32 v0, v0, v122
	flat_store_dwordx4 v[130:131], v[118:121] offset:512
	flat_store_dwordx4 v[130:131], v[114:117] offset:528
	v_pk_mul_f32 v[124:125], v[66:67], v[114:115]
	v_pk_mul_f32 v[118:119], v[70:71], v[118:119]
	v_pk_mul_f32 v[120:121], v[72:73], v[120:121]
	s_nop 1
	v_mov_b32_e32 v126, v0
	s_nop 1
	v_permlane16_swap_b32_e32 v0, v126
	v_add_f32_e32 v0, v0, v126
	v_mov_b32_e32 v114, v0
	s_nop 1
	v_permlane32_swap_b32_e32 v0, v114
	v_add_f32_e32 v0, v0, v114
	v_pk_mul_f32 v[122:123], v[68:69], v[116:117]
	v_cvt_pk_bf16_f32 v116, v118, v119
	v_cvt_pk_bf16_f32 v117, v120, v121
	v_cvt_pk_bf16_f32 v118, v124, v125
	s_nop 0
	v_cvt_pk_bf16_f32 v119, v122, v123
	flat_store_dwordx4 v[132:133], v[116:119] offset:256
	s_and_saveexec_b64 s[4:5], vcc
	s_cbranch_execz .LBB0_311
	flat_atomic_add_f32 v[186:187], v0 offset:64
.LBB0_311:
	s_or_b64 exec, exec, s[4:5]
	v_pk_fma_f32 v[112:113], v[112:113], 0.5, v[184:185] op_sel_hi:[1,0,1]
	v_pk_fma_f32 v[110:111], v[110:111], 0.5, v[182:183] op_sel_hi:[1,0,1]
	v_mul_f32_e32 v118, v113, v113
	v_mul_f32_e32 v0, v111, v111
	v_pk_fma_f32 v[106:107], v[106:107], 0.5, v[178:179] op_sel_hi:[1,0,1]
	v_fmac_f32_e32 v0, v110, v110
	v_fmac_f32_e32 v118, v112, v112
	v_add_f32_e32 v0, v0, v118
	v_mul_f32_e32 v118, v107, v107
	v_ashrrev_i32_e32 v241, 31, v240
	v_pk_fma_f32 v[108:109], v[108:109], 0.5, v[180:181] op_sel_hi:[1,0,1]
	v_fmac_f32_e32 v118, v106, v106
	v_lshlrev_b64 v[116:117], 11, v[240:241]
	v_add_f32_e32 v0, v118, v0
	v_mul_f32_e32 v118, v109, v109
	v_lshl_add_u64 v[114:115], v[232:233], 2, v[246:247]
	v_lshl_add_u64 v[116:117], s[58:59], 0, v[116:117]
	v_fmac_f32_e32 v118, v108, v108
	v_lshl_add_u64 v[116:117], v[232:233], 1, v[116:117]
	flat_store_dwordx4 v[114:115], v[110:113]
	flat_store_dwordx4 v[114:115], v[106:109] offset:16
	v_add_f32_e32 v0, v118, v0
	v_pk_mul_f32 v[112:113], v[80:81], v[112:113]
	v_pk_mul_f32 v[110:111], v[78:79], v[110:111]
	v_pk_mul_f32 v[118:119], v[76:77], v[108:109]
	v_pk_mul_f32 v[108:109], v[74:75], v[106:107]
	v_cvt_pk_bf16_f32 v106, v110, v111
	v_cvt_pk_bf16_f32 v107, v112, v113
	v_pk_fma_f32 v[104:105], v[104:105], 0.5, v[160:161] op_sel_hi:[1,0,1]
	v_pk_fma_f32 v[102:103], v[102:103], 0.5, v[158:159] op_sel_hi:[1,0,1]
	v_cvt_pk_bf16_f32 v108, v108, v109
	v_cvt_pk_bf16_f32 v109, v118, v119
	flat_store_dwordx4 v[116:117], v[106:109]
	v_pk_fma_f32 v[98:99], v[98:99], 0.5, v[154:155] op_sel_hi:[1,0,1]
	v_pk_fma_f32 v[100:101], v[100:101], 0.5, v[156:157] op_sel_hi:[1,0,1]
	v_mul_f32_e32 v106, v103, v103
	v_mul_f32_e32 v107, v105, v105
	v_fmac_f32_e32 v106, v102, v102
	v_fmac_f32_e32 v107, v104, v104
	v_add_f32_e32 v106, v106, v107
	v_mul_f32_e32 v107, v99, v99
	v_fmac_f32_e32 v107, v98, v98
	v_add_f32_e32 v106, v107, v106
	v_mul_f32_e32 v107, v101, v101
	v_fmac_f32_e32 v107, v100, v100
	v_add_f32_e32 v106, v107, v106
	v_add_f32_e32 v0, v0, v106
	flat_store_dwordx4 v[114:115], v[102:105] offset:512
	flat_store_dwordx4 v[114:115], v[98:101] offset:528
	v_pk_mul_f32 v[108:109], v[66:67], v[98:99]
	v_pk_mul_f32 v[102:103], v[70:71], v[102:103]
	v_pk_mul_f32 v[104:105], v[72:73], v[104:105]
	s_nop 1
	v_mov_b32_e32 v110, v0
	s_nop 1
	v_permlane16_swap_b32_e32 v0, v110
	v_add_f32_e32 v0, v0, v110
	v_mov_b32_e32 v98, v0
	s_nop 1
	v_permlane32_swap_b32_e32 v0, v98
	v_add_f32_e32 v0, v0, v98
	v_pk_mul_f32 v[106:107], v[68:69], v[100:101]
	v_cvt_pk_bf16_f32 v100, v102, v103
	v_cvt_pk_bf16_f32 v101, v104, v105
	v_cvt_pk_bf16_f32 v102, v108, v109
	s_nop 0
	v_cvt_pk_bf16_f32 v103, v106, v107
	flat_store_dwordx4 v[116:117], v[100:103] offset:256
	s_and_saveexec_b64 s[4:5], vcc
	s_cbranch_execz .LBB0_313
	flat_atomic_add_f32 v[186:187], v0 offset:128
; __device__ __forceinline__ float lane_xor(float v, int lane, int o) { return __builtin_bit_cast(float, __builtin_amdgcn_ds_bpermute((lane ^ o) << 2, __builtin_bit_cast(int, v))); }
; __device__ __forceinline__ unsigned cvt_pk_bf16(float lo, float hi) { unsigned r; asm volatile("v_cvt_pk_bf16_f32 %0, %1, %2" : "=v"(r) : "v"(lo), "v"(hi)); return r; }
;     __device__ __forceinline__ void operator()(const f32x4 (&acc)[2][2][4][2], const Unit& u, int wr, int wc, int fr_in, int fq_in) const {
;     ...
;             for (int m = 0; m < 4; ++m) { const int rw = row0 + ai * HALF + m * 16; hp[m] = hrow(LEAD, OUT, rw) + col0;
;                 const float* sp = hp[m];
;                 if (XP) { const int b = rw / LP, sl = rw - b * LP; if (sl >= 128) sp = (b < 2 ? XP + ((size_t)b * SEQ + (sl - 128)) * DM : XS + ((size_t)(b - 2) * SEQ + (sl - 128)) * DM) + col0; }
; #pragma unroll
;                 for (int bj = 0; bj < 2; ++bj) { hv[m][bj][0] = *(const f32x4*)(sp + bj * HALF); hv[m][bj][1] = *(const f32x4*)(sp + bj * HALF + 4); } }
;     ...
;             for (int m = 0; m < 4; ++m) {
;                 const int row = row0 + ai * HALF + m * 16;
;                 bf16_t* xp = XN + (size_t)row * DM + col0;
;                 float sq = 0.f;
; #pragma unroll
;                 for (int bj = 0; bj < 2; ++bj) {
;                     const f32x4 a = hv[m][bj][0] + acc[ai][bj][m][0] * alpha, b = hv[m][bj][1] + acc[ai][bj][m][1] * alpha;
;                     *(f32x4*)(hp[m] + bj * HALF) = a; *(f32x4*)(hp[m] + bj * HALF + 4) = b;
;                     sq += (a[0] * a[0] + a[1] * a[1]) + (a[2] * a[2] + a[3] * a[3]) + (b[0] * b[0] + b[1] * b[1]) + (b[2] * b[2] + b[3] * b[3]);
;                     const f32x4 xa = a * gv[bj][0], xb = b * gv[bj][1];
;                     u32x4 w; w.x = cvt_pk_bf16(xa[0], xa[1]); w.y = cvt_pk_bf16(xa[2], xa[3]); w.z = cvt_pk_bf16(xb[0], xb[1]); w.w = cvt_pk_bf16(xb[2], xb[3]);
;                     *(u32x4*)(xp + bj * HALF) = w;
;                 }
;                 sq += lane_xor(sq, lane, 16); sq += lane_xor(sq, lane, 32);
;                 if (fq == 0) atomicAdd(SSout + row, sq);
.LBB0_313:
	s_or_b64 exec, exec, s[4:5]
	v_pk_fma_f32 v[96:97], v[96:97], 0.5, v[176:177] op_sel_hi:[1,0,1]
	v_pk_fma_f32 v[94:95], v[94:95], 0.5, v[174:175] op_sel_hi:[1,0,1]
	v_mul_f32_e32 v102, v97, v97
	v_mul_f32_e32 v0, v95, v95
	v_pk_fma_f32 v[90:91], v[90:91], 0.5, v[166:167] op_sel_hi:[1,0,1]
	v_fmac_f32_e32 v0, v94, v94
	v_fmac_f32_e32 v102, v96, v96
	v_add_f32_e32 v0, v0, v102
	v_mul_f32_e32 v102, v91, v91
	v_ashrrev_i32_e32 v239, 31, v238
	v_pk_fma_f32 v[92:93], v[92:93], 0.5, v[168:169] op_sel_hi:[1,0,1]
	v_fmac_f32_e32 v102, v90, v90
	v_lshlrev_b64 v[100:101], 11, v[238:239]
	v_add_f32_e32 v0, v102, v0
	v_mul_f32_e32 v102, v93, v93
	v_lshl_add_u64 v[98:99], v[232:233], 2, v[242:243]
	v_lshl_add_u64 v[100:101], s[58:59], 0, v[100:101]
	v_fmac_f32_e32 v102, v92, v92
	v_lshl_add_u64 v[100:101], v[232:233], 1, v[100:101]
	flat_store_dwordx4 v[98:99], v[94:97]
	flat_store_dwordx4 v[98:99], v[90:93] offset:16
	v_add_f32_e32 v0, v102, v0
	v_pk_mul_f32 v[96:97], v[80:81], v[96:97]
	v_pk_mul_f32 v[94:95], v[78:79], v[94:95]
	v_pk_mul_f32 v[102:103], v[76:77], v[92:93]
	v_pk_mul_f32 v[92:93], v[74:75], v[90:91]
	v_cvt_pk_bf16_f32 v90, v94, v95
	v_cvt_pk_bf16_f32 v91, v96, v97
	v_pk_fma_f32 v[88:89], v[88:89], 0.5, v[152:153] op_sel_hi:[1,0,1]
	v_pk_fma_f32 v[86:87], v[86:87], 0.5, v[150:151] op_sel_hi:[1,0,1]
	v_cvt_pk_bf16_f32 v92, v92, v93
	v_cvt_pk_bf16_f32 v93, v102, v103
	flat_store_dwordx4 v[100:101], v[90:93]
	v_pk_fma_f32 v[82:83], v[82:83], 0.5, v[146:147] op_sel_hi:[1,0,1]
	v_pk_fma_f32 v[84:85], v[84:85], 0.5, v[148:149] op_sel_hi:[1,0,1]
	v_mul_f32_e32 v90, v87, v87
	v_mul_f32_e32 v91, v89, v89
	v_fmac_f32_e32 v90, v86, v86
	v_fmac_f32_e32 v91, v88, v88
	v_add_f32_e32 v90, v90, v91
	v_mul_f32_e32 v91, v83, v83
	v_fmac_f32_e32 v91, v82, v82
	v_add_f32_e32 v90, v91, v90
	v_mul_f32_e32 v91, v85, v85
	v_fmac_f32_e32 v91, v84, v84
	v_add_f32_e32 v90, v91, v90
	v_add_f32_e32 v0, v0, v90
	flat_store_dwordx4 v[98:99], v[86:89] offset:512
	flat_store_dwordx4 v[98:99], v[82:85] offset:528
	v_pk_mul_f32 v[92:93], v[66:67], v[82:83]
	v_pk_mul_f32 v[86:87], v[70:71], v[86:87]
	v_pk_mul_f32 v[88:89], v[72:73], v[88:89]
	s_nop 1
	v_mov_b32_e32 v94, v0
	s_nop 1
	v_permlane16_swap_b32_e32 v0, v94
	v_add_f32_e32 v0, v0, v94
	v_mov_b32_e32 v82, v0
	s_nop 1
	v_permlane32_swap_b32_e32 v0, v82
	v_add_f32_e32 v0, v0, v82
	v_pk_mul_f32 v[90:91], v[68:69], v[84:85]
	v_cvt_pk_bf16_f32 v84, v86, v87
	v_cvt_pk_bf16_f32 v85, v88, v89
	v_cvt_pk_bf16_f32 v86, v92, v93
	s_nop 0
	v_cvt_pk_bf16_f32 v87, v90, v91
	flat_store_dwordx4 v[100:101], v[84:87] offset:256
	s_and_saveexec_b64 s[4:5], vcc
	s_cbranch_execz .LBB0_315
	flat_atomic_add_f32 v[186:187], v0 offset:192
.LBB0_315:
	s_or_b64 exec, exec, s[4:5]
	v_add_u32_e32 v158, 0x80, v234
	v_mul_hi_i32 v0, v158, s33
	v_lshrrev_b32_e32 v82, 31, v0
	v_ashrrev_i32_e32 v0, 12, v0
	v_add_u32_e32 v84, v0, v82
	v_mul_i32_i24_e32 v0, 0xffffdf80, v84
	v_mad_i32_i24 v88, v84, s51, v158
	v_cmp_lt_i32_e64 s[4:5], s3, v88
	v_add_u32_e32 v0, v0, v234
	s_and_saveexec_b64 s[36:37], s[4:5]
	s_xor_b64 s[4:5], exec, s[36:37]
	v_ashrrev_i32_e32 v85, 31, v84
	v_lshlrev_b64 v[82:83], 25, v[84:85]
	v_lshl_add_u64 v[86:87], s[56:57], 0, v[82:83]
	v_mov_b64_e32 v[82:83], v[0:1]
	s_andn2_saveexec_b64 s[4:5], s[4:5]
	v_lshl_add_u32 v82, v84, 7, v88
	v_ashrrev_i32_e32 v83, 31, v82
	v_mov_b64_e32 v[86:87], s[18:19]
	s_or_b64 exec, exec, s[4:5]
	v_lshlrev_b64 v[82:83], 12, v[82:83]
	v_lshl_add_u64 v[82:83], v[86:87], 0, v[82:83]
	v_cmp_lt_i32_e64 s[4:5], s3, v88
	s_and_b64 s[4:5], s[22:23], s[4:5]
	v_mov_b64_e32 v[86:87], v[82:83]
	s_and_saveexec_b64 s[36:37], s[4:5]
	s_cbranch_execz .LBB0_325
	s_movk_i32 s4, 0x407f
	v_cmp_lt_i32_e64 s[4:5], s4, v234
	s_and_saveexec_b64 s[38:39], s[4:5]
	s_xor_b64 s[4:5], exec, s[38:39]
	v_add_u32_e32 v84, -2, v84
	v_mov_b32_e32 v85, v1
	v_lshlrev_b64 v[84:85], 25, v[84:85]
	v_lshl_add_u64 v[84:85], s[60:61], 0, v[84:85]
	v_lshlrev_b64 v[86:87], 12, v[0:1]
	v_lshl_add_u64 v[86:87], v[84:85], 0, v[86:87]
	s_andn2_saveexec_b64 s[4:5], s[4:5]
	v_ashrrev_i32_e32 v85, 31, v84
	v_lshlrev_b64 v[84:85], 25, v[84:85]
	v_lshl_add_u64 v[84:85], s[26:27], 0, v[84:85]
	v_lshlrev_b64 v[86:87], 12, v[0:1]
	v_lshl_add_u64 v[86:87], v[84:85], 0, v[86:87]
	s_or_b64 exec, exec, s[4:5]

; __device__ __forceinline__ float lane_xor(float v, int lane, int o) { return __builtin_bit_cast(float, __builtin_amdgcn_ds_bpermute((lane ^ o) << 2, __builtin_bit_cast(int, v))); }
; __device__ __forceinline__ unsigned cvt_pk_bf16(float lo, float hi) { unsigned r; asm volatile("v_cvt_pk_bf16_f32 %0, %1, %2" : "=v"(r) : "v"(lo), "v"(hi)); return r; }
;     __device__ __forceinline__ void operator()(const f32x4 (&acc)[2][2][4][2], const Unit& u, int wr, int wc, int fr_in, int fq_in) const {
;     ...
;             for (int m = 0; m < 4; ++m) {
;                 const int row = row0 + ai * HALF + m * 16;
;                 bf16_t* xp = XN + (size_t)row * DM + col0;
;                 float sq = 0.f;
; #pragma unroll
;                 for (int bj = 0; bj < 2; ++bj) {
;                     const f32x4 a = hv[m][bj][0] + acc[ai][bj][m][0] * alpha, b = hv[m][bj][1] + acc[ai][bj][m][1] * alpha;
;                     *(f32x4*)(hp[m] + bj * HALF) = a; *(f32x4*)(hp[m] + bj * HALF + 4) = b;
;                     sq += (a[0] * a[0] + a[1] * a[1]) + (a[2] * a[2] + a[3] * a[3]) + (b[0] * b[0] + b[1] * b[1]) + (b[2] * b[2] + b[3] * b[3]);
;                     const f32x4 xa = a * gv[bj][0], xb = b * gv[bj][1];
;                     u32x4 w; w.x = cvt_pk_bf16(xa[0], xa[1]); w.y = cvt_pk_bf16(xa[2], xa[3]); w.z = cvt_pk_bf16(xb[0], xb[1]); w.w = cvt_pk_bf16(xb[2], xb[3]);
;                     *(u32x4*)(xp + bj * HALF) = w;
;                 }
;                 sq += lane_xor(sq, lane, 16); sq += lane_xor(sq, lane, 32);
;                 if (fq == 0) atomicAdd(SSout + row, sq);
.LBB0_357:
	s_or_b64 exec, exec, s[4:5]
	v_pk_fma_f32 v[48:49], v[48:49], 0.5, v[128:129] op_sel_hi:[1,0,1]
	v_pk_fma_f32 v[46:47], v[46:47], 0.5, v[126:127] op_sel_hi:[1,0,1]
	v_mul_f32_e32 v54, v49, v49
	v_mul_f32_e32 v0, v47, v47
	v_pk_fma_f32 v[42:43], v[42:43], 0.5, v[122:123] op_sel_hi:[1,0,1]
	v_fmac_f32_e32 v0, v46, v46
	v_fmac_f32_e32 v54, v48, v48
	v_add_f32_e32 v0, v0, v54
	v_mul_f32_e32 v54, v43, v43
	v_ashrrev_i32_e32 v153, 31, v152
	v_pk_fma_f32 v[44:45], v[44:45], 0.5, v[124:125] op_sel_hi:[1,0,1]
	v_fmac_f32_e32 v54, v42, v42
	v_lshlrev_b64 v[52:53], 11, v[152:153]
	v_add_f32_e32 v0, v54, v0
	v_mul_f32_e32 v54, v45, v45
	v_lshl_add_u64 v[50:51], v[232:233], 2, v[156:157]
	v_lshl_add_u64 v[52:53], s[58:59], 0, v[52:53]
	v_fmac_f32_e32 v54, v44, v44
	v_lshl_add_u64 v[52:53], v[232:233], 1, v[52:53]
	flat_store_dwordx4 v[50:51], v[46:49]
	flat_store_dwordx4 v[50:51], v[42:45] offset:16
	v_add_f32_e32 v0, v54, v0
	v_pk_mul_f32 v[48:49], v[80:81], v[48:49]
	v_pk_mul_f32 v[46:47], v[78:79], v[46:47]
	v_pk_mul_f32 v[54:55], v[76:77], v[44:45]
	v_pk_mul_f32 v[44:45], v[74:75], v[42:43]
	v_cvt_pk_bf16_f32 v42, v46, v47
	v_cvt_pk_bf16_f32 v43, v48, v49
	v_pk_fma_f32 v[40:41], v[40:41], 0.5, v[112:113] op_sel_hi:[1,0,1]
	v_pk_fma_f32 v[38:39], v[38:39], 0.5, v[110:111] op_sel_hi:[1,0,1]
	v_cvt_pk_bf16_f32 v44, v44, v45
	v_cvt_pk_bf16_f32 v45, v54, v55
	flat_store_dwordx4 v[52:53], v[42:45]
	v_pk_fma_f32 v[34:35], v[34:35], 0.5, v[102:103] op_sel_hi:[1,0,1]
	v_pk_fma_f32 v[36:37], v[36:37], 0.5, v[104:105] op_sel_hi:[1,0,1]
	v_mul_f32_e32 v42, v39, v39
	v_mul_f32_e32 v43, v41, v41
	v_fmac_f32_e32 v42, v38, v38
	v_fmac_f32_e32 v43, v40, v40
	v_add_f32_e32 v42, v42, v43
	v_mul_f32_e32 v43, v35, v35
	v_fmac_f32_e32 v43, v34, v34
	v_add_f32_e32 v42, v43, v42
	v_mul_f32_e32 v43, v37, v37
	v_fmac_f32_e32 v43, v36, v36
	v_add_f32_e32 v42, v43, v42
	v_add_f32_e32 v0, v0, v42
	flat_store_dwordx4 v[50:51], v[38:41] offset:512
	flat_store_dwordx4 v[50:51], v[34:37] offset:528
	v_pk_mul_f32 v[44:45], v[66:67], v[34:35]
	v_pk_mul_f32 v[38:39], v[70:71], v[38:39]
	v_pk_mul_f32 v[40:41], v[72:73], v[40:41]
	s_nop 1
	v_mov_b32_e32 v46, v0
	s_nop 1
	v_permlane16_swap_b32_e32 v0, v46
	v_add_f32_e32 v0, v0, v46
	v_mov_b32_e32 v34, v0
	s_nop 1
	v_permlane32_swap_b32_e32 v0, v34
	v_add_f32_e32 v0, v0, v34
	v_pk_mul_f32 v[42:43], v[68:69], v[36:37]
	v_cvt_pk_bf16_f32 v36, v38, v39
	v_cvt_pk_bf16_f32 v37, v40, v41
	v_cvt_pk_bf16_f32 v38, v44, v45
	s_nop 0
	v_cvt_pk_bf16_f32 v39, v42, v43
	flat_store_dwordx4 v[52:53], v[36:39] offset:256
	s_and_saveexec_b64 s[4:5], vcc
	s_cbranch_execz .LBB0_359
	flat_atomic_add_f32 v[186:187], v0 offset:576
; __device__ __forceinline__ float lane_xor(float v, int lane, int o) { return __builtin_bit_cast(float, __builtin_amdgcn_ds_bpermute((lane ^ o) << 2, __builtin_bit_cast(int, v))); }
; __device__ __forceinline__ unsigned cvt_pk_bf16(float lo, float hi) { unsigned r; asm volatile("v_cvt_pk_bf16_f32 %0, %1, %2" : "=v"(r) : "v"(lo), "v"(hi)); return r; }
;     __device__ __forceinline__ void operator()(const f32x4 (&acc)[2][2][4][2], const Unit& u, int wr, int wc, int fr_in, int fq_in) const {
;     ...
;             for (int m = 0; m < 4; ++m) {
;                 const int row = row0 + ai * HALF + m * 16;
;                 bf16_t* xp = XN + (size_t)row * DM + col0;
;                 float sq = 0.f;
; #pragma unroll
;                 for (int bj = 0; bj < 2; ++bj) {
;                     const f32x4 a = hv[m][bj][0] + acc[ai][bj][m][0] * alpha, b = hv[m][bj][1] + acc[ai][bj][m][1] * alpha;
;                     *(f32x4*)(hp[m] + bj * HALF) = a; *(f32x4*)(hp[m] + bj * HALF + 4) = b;
;                     sq += (a[0] * a[0] + a[1] * a[1]) + (a[2] * a[2] + a[3] * a[3]) + (b[0] * b[0] + b[1] * b[1]) + (b[2] * b[2] + b[3] * b[3]);
;                     const f32x4 xa = a * gv[bj][0], xb = b * gv[bj][1];
;                     u32x4 w; w.x = cvt_pk_bf16(xa[0], xa[1]); w.y = cvt_pk_bf16(xa[2], xa[3]); w.z = cvt_pk_bf16(xb[0], xb[1]); w.w = cvt_pk_bf16(xb[2], xb[3]);
;                     *(u32x4*)(xp + bj * HALF) = w;
;                 }
;                 sq += lane_xor(sq, lane, 16); sq += lane_xor(sq, lane, 32);
;                 if (fq == 0) atomicAdd(SSout + row, sq);
.LBB0_359:
	s_or_b64 exec, exec, s[4:5]
	v_pk_fma_f32 v[32:33], v[32:33], 0.5, v[120:121] op_sel_hi:[1,0,1]
	v_pk_fma_f32 v[30:31], v[30:31], 0.5, v[118:119] op_sel_hi:[1,0,1]
	v_mul_f32_e32 v38, v33, v33
	v_mul_f32_e32 v0, v31, v31
	v_pk_fma_f32 v[26:27], v[26:27], 0.5, v[114:115] op_sel_hi:[1,0,1]
	v_fmac_f32_e32 v0, v30, v30
	v_fmac_f32_e32 v38, v32, v32
	v_add_f32_e32 v0, v0, v38
	v_mul_f32_e32 v38, v27, v27
	v_ashrrev_i32_e32 v149, 31, v148
	v_pk_fma_f32 v[28:29], v[28:29], 0.5, v[116:117] op_sel_hi:[1,0,1]
	v_fmac_f32_e32 v38, v26, v26
	v_lshlrev_b64 v[36:37], 11, v[148:149]
	v_add_f32_e32 v0, v38, v0
	v_mul_f32_e32 v38, v29, v29
	v_lshl_add_u64 v[34:35], v[232:233], 2, v[154:155]
	v_lshl_add_u64 v[36:37], s[58:59], 0, v[36:37]
	v_fmac_f32_e32 v38, v28, v28
	v_lshl_add_u64 v[36:37], v[232:233], 1, v[36:37]
	flat_store_dwordx4 v[34:35], v[30:33]
	flat_store_dwordx4 v[34:35], v[26:29] offset:16
	v_add_f32_e32 v0, v38, v0
	v_pk_mul_f32 v[32:33], v[80:81], v[32:33]
	v_pk_mul_f32 v[30:31], v[78:79], v[30:31]
	v_pk_mul_f32 v[38:39], v[76:77], v[28:29]
	v_pk_mul_f32 v[28:29], v[74:75], v[26:27]
	v_cvt_pk_bf16_f32 v26, v30, v31
	v_cvt_pk_bf16_f32 v27, v32, v33
	v_pk_fma_f32 v[24:25], v[24:25], 0.5, v[96:97] op_sel_hi:[1,0,1]
	v_pk_fma_f32 v[22:23], v[22:23], 0.5, v[94:95] op_sel_hi:[1,0,1]
	v_cvt_pk_bf16_f32 v28, v28, v29
	v_cvt_pk_bf16_f32 v29, v38, v39
	flat_store_dwordx4 v[36:37], v[26:29]
	v_pk_fma_f32 v[18:19], v[18:19], 0.5, v[90:91] op_sel_hi:[1,0,1]
	v_pk_fma_f32 v[20:21], v[20:21], 0.5, v[92:93] op_sel_hi:[1,0,1]
	v_mul_f32_e32 v26, v23, v23
	v_mul_f32_e32 v27, v25, v25
	v_fmac_f32_e32 v26, v22, v22
	v_fmac_f32_e32 v27, v24, v24
	v_add_f32_e32 v26, v26, v27
	v_mul_f32_e32 v27, v19, v19
	v_fmac_f32_e32 v27, v18, v18
	v_add_f32_e32 v26, v27, v26
	v_mul_f32_e32 v27, v21, v21
	v_fmac_f32_e32 v27, v20, v20
	v_add_f32_e32 v26, v27, v26
	v_add_f32_e32 v0, v0, v26
	flat_store_dwordx4 v[34:35], v[22:25] offset:512
	flat_store_dwordx4 v[34:35], v[18:21] offset:528
	v_pk_mul_f32 v[28:29], v[66:67], v[18:19]
	v_pk_mul_f32 v[22:23], v[70:71], v[22:23]
	v_pk_mul_f32 v[24:25], v[72:73], v[24:25]
	s_nop 1
	v_mov_b32_e32 v30, v0
	s_nop 1
	v_permlane16_swap_b32_e32 v0, v30
	v_add_f32_e32 v0, v0, v30
	v_mov_b32_e32 v18, v0
	s_nop 1
	v_permlane32_swap_b32_e32 v0, v18
	v_add_f32_e32 v0, v0, v18
	v_pk_mul_f32 v[26:27], v[68:69], v[20:21]
	v_cvt_pk_bf16_f32 v20, v22, v23
	v_cvt_pk_bf16_f32 v21, v24, v25
	v_cvt_pk_bf16_f32 v22, v28, v29
	s_nop 0
	v_cvt_pk_bf16_f32 v23, v26, v27
	flat_store_dwordx4 v[36:37], v[20:23] offset:256
	s_and_saveexec_b64 s[4:5], vcc
	s_cbranch_execz .LBB0_361
	flat_atomic_add_f32 v[186:187], v0 offset:640
.LBB0_361:
	s_or_b64 exec, exec, s[4:5]
	v_pk_fma_f32 v[16:17], v[16:17], 0.5, v[108:109] op_sel_hi:[1,0,1]
	v_pk_fma_f32 v[14:15], v[14:15], 0.5, v[106:107] op_sel_hi:[1,0,1]
	v_mul_f32_e32 v22, v17, v17
	v_mul_f32_e32 v0, v15, v15
	v_pk_fma_f32 v[10:11], v[10:11], 0.5, v[98:99] op_sel_hi:[1,0,1]
	v_fmac_f32_e32 v0, v14, v14
	v_fmac_f32_e32 v22, v16, v16
	v_add_f32_e32 v0, v0, v22
	v_mul_f32_e32 v22, v11, v11
	v_ashrrev_i32_e32 v147, 31, v146
	v_pk_fma_f32 v[12:13], v[12:13], 0.5, v[100:101] op_sel_hi:[1,0,1]
	v_fmac_f32_e32 v22, v10, v10
	v_lshlrev_b64 v[20:21], 11, v[146:147]
	v_add_f32_e32 v0, v22, v0
	v_mul_f32_e32 v22, v13, v13
	v_lshl_add_u64 v[18:19], v[232:233], 2, v[150:151]
	v_lshl_add_u64 v[20:21], s[58:59], 0, v[20:21]
	v_fmac_f32_e32 v22, v12, v12
	v_lshl_add_u64 v[20:21], v[232:233], 1, v[20:21]
	flat_store_dwordx4 v[18:19], v[14:17]
	flat_store_dwordx4 v[18:19], v[10:13] offset:16
	v_add_f32_e32 v0, v22, v0
	v_pk_mul_f32 v[16:17], v[80:81], v[16:17]
	v_pk_mul_f32 v[14:15], v[78:79], v[14:15]
	v_pk_mul_f32 v[22:23], v[76:77], v[12:13]
	v_pk_mul_f32 v[12:13], v[74:75], v[10:11]
	v_cvt_pk_bf16_f32 v10, v14, v15
	v_cvt_pk_bf16_f32 v11, v16, v17
	v_pk_fma_f32 v[8:9], v[8:9], 0.5, v[88:89] op_sel_hi:[1,0,1]
	v_pk_fma_f32 v[6:7], v[6:7], 0.5, v[86:87] op_sel_hi:[1,0,1]
	v_cvt_pk_bf16_f32 v12, v12, v13
	v_cvt_pk_bf16_f32 v13, v22, v23
	flat_store_dwordx4 v[20:21], v[10:13]
	v_pk_fma_f32 v[2:3], v[2:3], 0.5, v[82:83] op_sel_hi:[1,0,1]
	v_pk_fma_f32 v[4:5], v[4:5], 0.5, v[84:85] op_sel_hi:[1,0,1]
	v_mul_f32_e32 v10, v7, v7
	v_mul_f32_e32 v11, v9, v9
	v_fmac_f32_e32 v10, v6, v6
	v_fmac_f32_e32 v11, v8, v8
	v_add_f32_e32 v10, v10, v11
	v_mul_f32_e32 v11, v3, v3
	v_fmac_f32_e32 v11, v2, v2
	v_add_f32_e32 v10, v11, v10
	v_mul_f32_e32 v11, v5, v5
	v_fmac_f32_e32 v11, v4, v4
	v_add_f32_e32 v10, v11, v10
	v_add_f32_e32 v0, v0, v10
	flat_store_dwordx4 v[18:19], v[6:9] offset:512
	flat_store_dwordx4 v[18:19], v[2:5] offset:528
	v_pk_mul_f32 v[12:13], v[66:67], v[2:3]
	v_pk_mul_f32 v[6:7], v[70:71], v[6:7]
	v_pk_mul_f32 v[8:9], v[72:73], v[8:9]
	s_nop 1
	v_mov_b32_e32 v14, v0
	s_nop 1
	v_permlane16_swap_b32_e32 v0, v14
	v_add_f32_e32 v0, v0, v14
	v_mov_b32_e32 v2, v0
	s_nop 1
	v_permlane32_swap_b32_e32 v0, v2
	v_add_f32_e32 v0, v0, v2
	v_pk_mul_f32 v[10:11], v[68:69], v[4:5]
	v_cvt_pk_bf16_f32 v4, v6, v7
	v_cvt_pk_bf16_f32 v5, v8, v9
	v_cvt_pk_bf16_f32 v6, v12, v13
	s_nop 0
	v_cvt_pk_bf16_f32 v7, v10, v11
	flat_store_dwordx4 v[20:21], v[4:7] offset:256
	s_and_saveexec_b64 s[4:5], vcc
	s_cbranch_execz .LBB0_363
	flat_atomic_add_f32 v[186:187], v0 offset:704

; __device__ __forceinline__ float lane_xor(float v, int lane, int o) { return __builtin_bit_cast(float, __builtin_amdgcn_ds_bpermute((lane ^ o) << 2, __builtin_bit_cast(int, v))); }
; __device__ __forceinline__ unsigned cvt_pk_bf16(float lo, float hi) { unsigned r; asm volatile("v_cvt_pk_bf16_f32 %0, %1, %2" : "=v"(r) : "v"(lo), "v"(hi)); return r; }
;     __device__ __forceinline__ void operator()(const f32x4 (&acc)[2][2][4][2], const Unit& u, int wr, int wc, int fr_in, int fq_in) const {
;     ...
;             for (int m = 0; m < 4; ++m) {
;                 const int row = row0 + ai * HALF + m * 16;
;                 bf16_t* xp = XN + (size_t)row * DM + col0;
;                 float sq = 0.f;
; #pragma unroll
;                 for (int bj = 0; bj < 2; ++bj) {
;                     const f32x4 a = hv[m][bj][0] + acc[ai][bj][m][0] * alpha, b = hv[m][bj][1] + acc[ai][bj][m][1] * alpha;
;                     *(f32x4*)(hp[m] + bj * HALF) = a; *(f32x4*)(hp[m] + bj * HALF + 4) = b;
;                     sq += (a[0] * a[0] + a[1] * a[1]) + (a[2] * a[2] + a[3] * a[3]) + (b[0] * b[0] + b[1] * b[1]) + (b[2] * b[2] + b[3] * b[3]);
;                     const f32x4 xa = a * gv[bj][0], xb = b * gv[bj][1];
;                     u32x4 w; w.x = cvt_pk_bf16(xa[0], xa[1]); w.y = cvt_pk_bf16(xa[2], xa[3]); w.z = cvt_pk_bf16(xb[0], xb[1]); w.w = cvt_pk_bf16(xb[2], xb[3]);
;                     *(u32x4*)(xp + bj * HALF) = w;
;                 }
;                 sq += lane_xor(sq, lane, 16); sq += lane_xor(sq, lane, 32);
;                 if (fq == 0) atomicAdd(SSout + row, sq);
.LBB0_1100:
	s_or_b64 exec, exec, s[4:5]
	v_pk_add_f32 v[128:129], v[192:193], v[128:129]
	v_pk_add_f32 v[126:127], v[190:191], v[126:127]
	v_mul_f32_e32 v132, v129, v129
	v_mul_f32_e32 v0, v127, v127
	v_pk_add_f32 v[122:123], v[186:187], v[122:123]
	v_fmac_f32_e32 v0, v126, v126
	v_fmac_f32_e32 v132, v128, v128
	v_add_f32_e32 v0, v0, v132
	v_mul_f32_e32 v132, v123, v123
	v_ashrrev_i32_e32 v247, 31, v246
	v_pk_add_f32 v[124:125], v[188:189], v[124:125]
	v_fmac_f32_e32 v132, v122, v122
	v_lshlrev_b64 v[130:131], 11, v[246:247]
	v_add_f32_e32 v0, v132, v0
	v_mul_f32_e32 v132, v125, v125
	v_lshl_add_u64 v[130:131], s[58:59], 0, v[130:131]
	v_fmac_f32_e32 v132, v124, v124
	v_lshl_add_u64 v[130:131], v[232:233], 1, v[130:131]
	flat_store_dwordx4 v[244:245], v[126:129]
	flat_store_dwordx4 v[244:245], v[122:125] offset:16
	v_add_f32_e32 v0, v132, v0
	v_pk_mul_f32 v[128:129], v[80:81], v[128:129]
	v_pk_mul_f32 v[126:127], v[78:79], v[126:127]
	v_pk_mul_f32 v[132:133], v[76:77], v[124:125]
	v_pk_mul_f32 v[124:125], v[74:75], v[122:123]
	v_cvt_pk_bf16_f32 v122, v126, v127
	v_cvt_pk_bf16_f32 v123, v128, v129
	v_pk_add_f32 v[120:121], v[184:185], v[120:121]
	v_pk_add_f32 v[118:119], v[182:183], v[118:119]
	v_cvt_pk_bf16_f32 v124, v124, v125
	v_cvt_pk_bf16_f32 v125, v132, v133
	flat_store_dwordx4 v[130:131], v[122:125]
	v_pk_add_f32 v[114:115], v[178:179], v[114:115]
	v_pk_add_f32 v[116:117], v[180:181], v[116:117]
	v_mul_f32_e32 v122, v119, v119
	v_mul_f32_e32 v123, v121, v121
	v_fmac_f32_e32 v122, v118, v118
	v_fmac_f32_e32 v123, v120, v120
	v_add_f32_e32 v122, v122, v123
	v_mul_f32_e32 v123, v115, v115
	v_fmac_f32_e32 v123, v114, v114
	v_add_f32_e32 v122, v123, v122
	v_mul_f32_e32 v123, v117, v117
	v_fmac_f32_e32 v123, v116, v116
	v_add_f32_e32 v122, v123, v122
	v_add_f32_e32 v0, v0, v122
	flat_store_dwordx4 v[244:245], v[118:121] offset:512
	flat_store_dwordx4 v[244:245], v[114:117] offset:528
	v_pk_mul_f32 v[124:125], v[66:67], v[114:115]
	v_pk_mul_f32 v[118:119], v[70:71], v[118:119]
	v_pk_mul_f32 v[120:121], v[72:73], v[120:121]
	s_nop 1
	v_mov_b32_e32 v126, v0
	s_nop 1
	v_permlane16_swap_b32_e32 v0, v126
	v_add_f32_e32 v0, v0, v126
	v_mov_b32_e32 v114, v0
	s_nop 1
	v_permlane32_swap_b32_e32 v0, v114
	v_add_f32_e32 v0, v0, v114
	v_pk_mul_f32 v[122:123], v[68:69], v[116:117]
	v_cvt_pk_bf16_f32 v116, v118, v119
	v_cvt_pk_bf16_f32 v117, v120, v121
	v_cvt_pk_bf16_f32 v118, v124, v125
	s_nop 0
	v_cvt_pk_bf16_f32 v119, v122, v123
	flat_store_dwordx4 v[130:131], v[116:119] offset:256
	s_and_saveexec_b64 s[4:5], vcc
	s_cbranch_execz .LBB0_1102
	flat_atomic_add_f32 v[194:195], v0 offset:64
.LBB0_1102:
	s_or_b64 exec, exec, s[4:5]
	v_pk_add_f32 v[112:113], v[176:177], v[112:113]
	v_pk_add_f32 v[110:111], v[174:175], v[110:111]
	v_mul_f32_e32 v116, v113, v113
	v_mul_f32_e32 v0, v111, v111
	v_pk_add_f32 v[106:107], v[170:171], v[106:107]
	v_fmac_f32_e32 v0, v110, v110
	v_fmac_f32_e32 v116, v112, v112
	v_add_f32_e32 v0, v0, v116
	v_mul_f32_e32 v116, v107, v107
	v_ashrrev_i32_e32 v243, 31, v242
	v_pk_add_f32 v[108:109], v[172:173], v[108:109]
	v_fmac_f32_e32 v116, v106, v106
	v_lshlrev_b64 v[114:115], 11, v[242:243]
	v_add_f32_e32 v0, v116, v0
	v_mul_f32_e32 v116, v109, v109
	v_lshl_add_u64 v[114:115], s[58:59], 0, v[114:115]
	v_fmac_f32_e32 v116, v108, v108
	v_lshl_add_u64 v[114:115], v[232:233], 1, v[114:115]
	flat_store_dwordx4 v[240:241], v[110:113]
	flat_store_dwordx4 v[240:241], v[106:109] offset:16
	v_add_f32_e32 v0, v116, v0
	v_pk_mul_f32 v[112:113], v[80:81], v[112:113]
	v_pk_mul_f32 v[110:111], v[78:79], v[110:111]
	v_pk_mul_f32 v[116:117], v[76:77], v[108:109]
	v_pk_mul_f32 v[108:109], v[74:75], v[106:107]
	v_cvt_pk_bf16_f32 v106, v110, v111
	v_cvt_pk_bf16_f32 v107, v112, v113
	v_pk_add_f32 v[104:105], v[168:169], v[104:105]
	v_pk_add_f32 v[102:103], v[166:167], v[102:103]
	v_cvt_pk_bf16_f32 v108, v108, v109
	v_cvt_pk_bf16_f32 v109, v116, v117
	flat_store_dwordx4 v[114:115], v[106:109]
	v_pk_add_f32 v[98:99], v[162:163], v[98:99]
	v_pk_add_f32 v[100:101], v[164:165], v[100:101]
	v_mul_f32_e32 v106, v103, v103
	v_mul_f32_e32 v107, v105, v105
	v_fmac_f32_e32 v106, v102, v102
	v_fmac_f32_e32 v107, v104, v104
	v_add_f32_e32 v106, v106, v107
	v_mul_f32_e32 v107, v99, v99
	v_fmac_f32_e32 v107, v98, v98
	v_add_f32_e32 v106, v107, v106
	v_mul_f32_e32 v107, v101, v101
	v_fmac_f32_e32 v107, v100, v100
	v_add_f32_e32 v106, v107, v106
	v_add_f32_e32 v0, v0, v106
	flat_store_dwordx4 v[240:241], v[102:105] offset:512
	flat_store_dwordx4 v[240:241], v[98:101] offset:528
	v_pk_mul_f32 v[108:109], v[66:67], v[98:99]
	v_pk_mul_f32 v[102:103], v[70:71], v[102:103]
	v_pk_mul_f32 v[104:105], v[72:73], v[104:105]
	s_nop 1
	v_mov_b32_e32 v110, v0
	s_nop 1
	v_permlane16_swap_b32_e32 v0, v110
	v_add_f32_e32 v0, v0, v110
	v_mov_b32_e32 v98, v0
	s_nop 1
	v_permlane32_swap_b32_e32 v0, v98
	v_add_f32_e32 v0, v0, v98
	v_pk_mul_f32 v[106:107], v[68:69], v[100:101]
	v_cvt_pk_bf16_f32 v100, v102, v103
	v_cvt_pk_bf16_f32 v101, v104, v105
	v_cvt_pk_bf16_f32 v102, v108, v109
	s_nop 0
	v_cvt_pk_bf16_f32 v103, v106, v107
	flat_store_dwordx4 v[114:115], v[100:103] offset:256
	s_and_saveexec_b64 s[4:5], vcc
	s_cbranch_execz .LBB0_1104
	flat_atomic_add_f32 v[194:195], v0 offset:128
; __device__ __forceinline__ float lane_xor(float v, int lane, int o) { return __builtin_bit_cast(float, __builtin_amdgcn_ds_bpermute((lane ^ o) << 2, __builtin_bit_cast(int, v))); }
; __device__ __forceinline__ unsigned cvt_pk_bf16(float lo, float hi) { unsigned r; asm volatile("v_cvt_pk_bf16_f32 %0, %1, %2" : "=v"(r) : "v"(lo), "v"(hi)); return r; }
;     __device__ __forceinline__ void operator()(const f32x4 (&acc)[2][2][4][2], const Unit& u, int wr, int wc, int fr_in, int fq_in) const {
;     ...
;             for (int m = 0; m < 4; ++m) { const int rw = row0 + ai * HALF + m * 16; hp[m] = hrow(LEAD, OUT, rw) + col0;
;                 const float* sp = hp[m];
;                 if (XP) { const int b = rw / LP, sl = rw - b * LP; if (sl >= 128) sp = (b < 2 ? XP + ((size_t)b * SEQ + (sl - 128)) * DM : XS + ((size_t)(b - 2) * SEQ + (sl - 128)) * DM) + col0; }
; #pragma unroll
;                 for (int bj = 0; bj < 2; ++bj) { hv[m][bj][0] = *(const f32x4*)(sp + bj * HALF); hv[m][bj][1] = *(const f32x4*)(sp + bj * HALF + 4); } }
;     ...
;             for (int m = 0; m < 4; ++m) {
;                 const int row = row0 + ai * HALF + m * 16;
;                 bf16_t* xp = XN + (size_t)row * DM + col0;
;                 float sq = 0.f;
; #pragma unroll
;                 for (int bj = 0; bj < 2; ++bj) {
;                     const f32x4 a = hv[m][bj][0] + acc[ai][bj][m][0] * alpha, b = hv[m][bj][1] + acc[ai][bj][m][1] * alpha;
;                     *(f32x4*)(hp[m] + bj * HALF) = a; *(f32x4*)(hp[m] + bj * HALF + 4) = b;
;                     sq += (a[0] * a[0] + a[1] * a[1]) + (a[2] * a[2] + a[3] * a[3]) + (b[0] * b[0] + b[1] * b[1]) + (b[2] * b[2] + b[3] * b[3]);
;                     const f32x4 xa = a * gv[bj][0], xb = b * gv[bj][1];
;                     u32x4 w; w.x = cvt_pk_bf16(xa[0], xa[1]); w.y = cvt_pk_bf16(xa[2], xa[3]); w.z = cvt_pk_bf16(xb[0], xb[1]); w.w = cvt_pk_bf16(xb[2], xb[3]);
;                     *(u32x4*)(xp + bj * HALF) = w;
;                 }
;                 sq += lane_xor(sq, lane, 16); sq += lane_xor(sq, lane, 32);
;                 if (fq == 0) atomicAdd(SSout + row, sq);
.LBB0_1104:
	s_or_b64 exec, exec, s[4:5]
	v_pk_add_f32 v[96:97], v[160:161], v[96:97]
	v_pk_add_f32 v[94:95], v[158:159], v[94:95]
	v_mul_f32_e32 v100, v97, v97
	v_mul_f32_e32 v0, v95, v95
	v_pk_add_f32 v[90:91], v[154:155], v[90:91]
	v_fmac_f32_e32 v0, v94, v94
	v_fmac_f32_e32 v100, v96, v96
	v_add_f32_e32 v0, v0, v100
	v_mul_f32_e32 v100, v91, v91
	v_ashrrev_i32_e32 v239, 31, v238
	v_pk_add_f32 v[92:93], v[156:157], v[92:93]
	v_fmac_f32_e32 v100, v90, v90
	v_lshlrev_b64 v[98:99], 11, v[238:239]
	v_add_f32_e32 v0, v100, v0
	v_mul_f32_e32 v100, v93, v93
	v_lshl_add_u64 v[98:99], s[58:59], 0, v[98:99]
	v_fmac_f32_e32 v100, v92, v92
	v_lshl_add_u64 v[98:99], v[232:233], 1, v[98:99]
	flat_store_dwordx4 v[236:237], v[94:97]
	flat_store_dwordx4 v[236:237], v[90:93] offset:16
	v_add_f32_e32 v0, v100, v0
	v_pk_mul_f32 v[96:97], v[80:81], v[96:97]
	v_pk_mul_f32 v[94:95], v[78:79], v[94:95]
	v_pk_mul_f32 v[100:101], v[76:77], v[92:93]
	v_pk_mul_f32 v[92:93], v[74:75], v[90:91]
	v_cvt_pk_bf16_f32 v90, v94, v95
	v_cvt_pk_bf16_f32 v91, v96, v97
	v_pk_add_f32 v[88:89], v[152:153], v[88:89]
	v_pk_add_f32 v[86:87], v[150:151], v[86:87]
	v_cvt_pk_bf16_f32 v92, v92, v93
	v_cvt_pk_bf16_f32 v93, v100, v101
	flat_store_dwordx4 v[98:99], v[90:93]
	v_pk_add_f32 v[82:83], v[146:147], v[82:83]
	v_pk_add_f32 v[84:85], v[148:149], v[84:85]
	v_mul_f32_e32 v90, v87, v87
	v_mul_f32_e32 v91, v89, v89
	v_fmac_f32_e32 v90, v86, v86
	v_fmac_f32_e32 v91, v88, v88
	v_add_f32_e32 v90, v90, v91
	v_mul_f32_e32 v91, v83, v83
	v_fmac_f32_e32 v91, v82, v82
	v_add_f32_e32 v90, v91, v90
	v_mul_f32_e32 v91, v85, v85
	v_fmac_f32_e32 v91, v84, v84
	v_add_f32_e32 v90, v91, v90
	v_add_f32_e32 v0, v0, v90
	flat_store_dwordx4 v[236:237], v[86:89] offset:512
	flat_store_dwordx4 v[236:237], v[82:85] offset:528
	v_pk_mul_f32 v[92:93], v[66:67], v[82:83]
	v_pk_mul_f32 v[86:87], v[70:71], v[86:87]
	v_pk_mul_f32 v[88:89], v[72:73], v[88:89]
	s_nop 1
	v_mov_b32_e32 v94, v0
	s_nop 1
	v_permlane16_swap_b32_e32 v0, v94
	v_add_f32_e32 v0, v0, v94
	v_mov_b32_e32 v82, v0
	s_nop 1
	v_permlane32_swap_b32_e32 v0, v82
	v_add_f32_e32 v0, v0, v82
	v_pk_mul_f32 v[90:91], v[68:69], v[84:85]
	v_cvt_pk_bf16_f32 v84, v86, v87
	v_cvt_pk_bf16_f32 v85, v88, v89
	v_cvt_pk_bf16_f32 v86, v92, v93
	s_nop 0
	v_cvt_pk_bf16_f32 v87, v90, v91
	flat_store_dwordx4 v[98:99], v[84:87] offset:256
	s_and_saveexec_b64 s[4:5], vcc
	s_cbranch_execz .LBB0_1106
	flat_atomic_add_f32 v[194:195], v0 offset:192
.LBB0_1106:
	s_or_b64 exec, exec, s[4:5]
	v_add_u32_e32 v160, 0x80, v234
	v_mul_hi_i32 v0, v160, s33
	v_lshrrev_b32_e32 v82, 31, v0
	v_ashrrev_i32_e32 v0, 12, v0
	v_add_u32_e32 v82, v0, v82
	v_mad_i32_i24 v0, v82, s51, v160
	v_cmp_lt_i32_e64 s[4:5], s3, v0
	s_and_saveexec_b64 s[36:37], s[4:5]
	s_xor_b64 s[4:5], exec, s[36:37]
	v_mul_i32_i24_e32 v0, 0xffffdf80, v82
	v_ashrrev_i32_e32 v83, 31, v82
	v_add_u32_e32 v0, v0, v234
	v_lshlrev_b64 v[82:83], 25, v[82:83]
	v_lshl_add_u64 v[86:87], s[56:57], 0, v[82:83]
	v_mov_b64_e32 v[84:85], v[0:1]
	s_andn2_saveexec_b64 s[4:5], s[4:5]
	v_lshl_add_u32 v84, v82, 7, v0
	v_ashrrev_i32_e32 v85, 31, v84
	v_mov_b64_e32 v[86:87], s[18:19]
	s_or_b64 exec, exec, s[4:5]
	v_lshlrev_b64 v[82:83], 12, v[84:85]
	v_lshl_add_u64 v[82:83], v[86:87], 0, v[82:83]
	v_lshl_add_u64 v[158:159], v[232:233], 2, v[82:83]
	flat_load_dwordx4 v[142:145], v[158:159]
	flat_load_dwordx4 v[138:141], v[158:159] offset:16
	flat_load_dwordx4 v[134:137], v[158:159] offset:512
	flat_load_dwordx4 v[130:133], v[158:159] offset:528
	v_add_u32_e32 v156, 0x90, v234
	v_mul_hi_i32 v0, v156, s33
	v_lshrrev_b32_e32 v82, 31, v0
	v_ashrrev_i32_e32 v0, 12, v0
	v_add_u32_e32 v82, v0, v82
	v_mad_i32_i24 v0, v82, s51, v156
	v_cmp_lt_i32_e64 s[4:5], s3, v0
	s_and_saveexec_b64 s[36:37], s[4:5]
	s_xor_b64 s[4:5], exec, s[36:37]
	v_ashrrev_i32_e32 v83, 31, v82
	v_add_u32_e32 v0, 0xffffff80, v0
	v_lshlrev_b64 v[82:83], 25, v[82:83]
	v_lshl_add_u64 v[86:87], s[56:57], 0, v[82:83]
	v_mov_b64_e32 v[84:85], v[0:1]
	s_andn2_saveexec_b64 s[4:5], s[4:5]
	v_lshl_add_u32 v84, v82, 7, v0
	v_ashrrev_i32_e32 v85, 31, v84
	v_mov_b64_e32 v[86:87], s[18:19]
	s_or_b64 exec, exec, s[4:5]
	v_lshlrev_b64 v[82:83], 12, v[84:85]
	v_lshl_add_u64 v[82:83], v[86:87], 0, v[82:83]
	v_lshl_add_u64 v[154:155], v[232:233], 2, v[82:83]
	flat_load_dwordx4 v[126:129], v[154:155]
	flat_load_dwordx4 v[122:125], v[154:155] offset:16
	flat_load_dwordx4 v[118:121], v[154:155] offset:512
	flat_load_dwordx4 v[114:117], v[154:155] offset:528
	v_add_u32_e32 v152, 0xa0, v234
	v_mul_hi_i32 v0, v152, s33
	v_lshrrev_b32_e32 v82, 31, v0
	v_ashrrev_i32_e32 v0, 12, v0
	v_add_u32_e32 v82, v0, v82
	v_mad_i32_i24 v0, v82, s51, v152
	v_cmp_lt_i32_e64 s[4:5], s3, v0
	s_and_saveexec_b64 s[36:37], s[4:5]
	s_xor_b64 s[4:5], exec, s[36:37]
	v_ashrrev_i32_e32 v83, 31, v82
	v_add_u32_e32 v0, 0xffffff80, v0
	v_lshlrev_b64 v[82:83], 25, v[82:83]
	v_lshl_add_u64 v[86:87], s[56:57], 0, v[82:83]
	v_mov_b64_e32 v[84:85], v[0:1]
	s_andn2_saveexec_b64 s[4:5], s[4:5]
	v_lshl_add_u32 v84, v82, 7, v0
	v_ashrrev_i32_e32 v85, 31, v84
	v_mov_b64_e32 v[86:87], s[18:19]
	s_or_b64 exec, exec, s[4:5]
	v_lshlrev_b64 v[82:83], 12, v[84:85]
	v_lshl_add_u64 v[82:83], v[86:87], 0, v[82:83]
	v_lshl_add_u64 v[150:151], v[232:233], 2, v[82:83]
	flat_load_dwordx4 v[110:113], v[150:151]
	flat_load_dwordx4 v[106:109], v[150:151] offset:16
	flat_load_dwordx4 v[102:105], v[150:151] offset:512
	flat_load_dwordx4 v[98:101], v[150:151] offset:528
	v_add_u32_e32 v148, 0xb0, v234
	v_mul_hi_i32 v0, v148, s33
	v_lshrrev_b32_e32 v82, 31, v0
	v_ashrrev_i32_e32 v0, 12, v0
	v_add_u32_e32 v82, v0, v82
	v_mad_i32_i24 v0, v82, s51, v148
	v_cmp_lt_i32_e64 s[4:5], s3, v0
	s_and_saveexec_b64 s[36:37], s[4:5]
	s_xor_b64 s[4:5], exec, s[36:37]
	v_ashrrev_i32_e32 v83, 31, v82
	v_add_u32_e32 v0, 0xffffff80, v0
	v_lshlrev_b64 v[82:83], 25, v[82:83]
	v_lshl_add_u64 v[86:87], s[56:57], 0, v[82:83]
	v_mov_b64_e32 v[84:85], v[0:1]
	s_andn2_saveexec_b64 s[4:5], s[4:5]
	v_lshl_add_u32 v84, v82, 7, v0
	v_ashrrev_i32_e32 v85, 31, v84
	v_mov_b64_e32 v[86:87], s[18:19]
	s_or_b64 exec, exec, s[4:5]
	v_lshlrev_b64 v[82:83], 12, v[84:85]
	v_lshl_add_u64 v[82:83], v[86:87], 0, v[82:83]
	v_lshl_add_u64 v[146:147], v[232:233], 2, v[82:83]
	flat_load_dwordx4 v[94:97], v[146:147]
	flat_load_dwordx4 v[90:93], v[146:147] offset:16
	flat_load_dwordx4 v[86:89], v[146:147] offset:512
	flat_load_dwordx4 v[82:85], v[146:147] offset:528
	s_waitcnt vmcnt(0) lgkmcnt(0)
; __device__ __forceinline__ float lane_xor(float v, int lane, int o) { return __builtin_bit_cast(float, __builtin_amdgcn_ds_bpermute((lane ^ o) << 2, __builtin_bit_cast(int, v))); }
; __device__ __forceinline__ unsigned cvt_pk_bf16(float lo, float hi) { unsigned r; asm volatile("v_cvt_pk_bf16_f32 %0, %1, %2" : "=v"(r) : "v"(lo), "v"(hi)); return r; }
;     __device__ __forceinline__ void operator()(const f32x4 (&acc)[2][2][4][2], const Unit& u, int wr, int wc, int fr_in, int fq_in) const {
;     ...
;             for (int m = 0; m < 4; ++m) {
;                 const int row = row0 + ai * HALF + m * 16;
;                 bf16_t* xp = XN + (size_t)row * DM + col0;
;                 float sq = 0.f;
; #pragma unroll
;                 for (int bj = 0; bj < 2; ++bj) {
;                     const f32x4 a = hv[m][bj][0] + acc[ai][bj][m][0] * alpha, b = hv[m][bj][1] + acc[ai][bj][m][1] * alpha;
;                     *(f32x4*)(hp[m] + bj * HALF) = a; *(f32x4*)(hp[m] + bj * HALF + 4) = b;
;                     sq += (a[0] * a[0] + a[1] * a[1]) + (a[2] * a[2] + a[3] * a[3]) + (b[0] * b[0] + b[1] * b[1]) + (b[2] * b[2] + b[3] * b[3]);
;                     const f32x4 xa = a * gv[bj][0], xb = b * gv[bj][1];
;                     u32x4 w; w.x = cvt_pk_bf16(xa[0], xa[1]); w.y = cvt_pk_bf16(xa[2], xa[3]); w.z = cvt_pk_bf16(xb[0], xb[1]); w.w = cvt_pk_bf16(xb[2], xb[3]);
;                     *(u32x4*)(xp + bj * HALF) = w;
;                 }
;                 sq += lane_xor(sq, lane, 16); sq += lane_xor(sq, lane, 32);
;                 if (fq == 0) atomicAdd(SSout + row, sq);
	v_pk_add_f32 v[64:65], v[144:145], v[64:65]
	v_pk_add_f32 v[62:63], v[142:143], v[62:63]
	v_pk_add_f32 v[58:59], v[138:139], v[58:59]
	v_mul_f32_e32 v0, v63, v63
	v_mul_f32_e32 v138, v65, v65
	v_fmac_f32_e32 v0, v62, v62
	v_fmac_f32_e32 v138, v64, v64
	v_add_f32_e32 v0, v0, v138
	v_mul_f32_e32 v138, v59, v59
	v_ashrrev_i32_e32 v161, 31, v160
	v_pk_add_f32 v[60:61], v[140:141], v[60:61]
	v_fmac_f32_e32 v138, v58, v58
	v_lshlrev_b64 v[160:161], 11, v[160:161]
	v_add_f32_e32 v0, v138, v0
	v_mul_f32_e32 v138, v61, v61
	v_lshl_add_u64 v[160:161], s[58:59], 0, v[160:161]
	v_fmac_f32_e32 v138, v60, v60
	v_lshl_add_u64 v[160:161], v[232:233], 1, v[160:161]
	flat_store_dwordx4 v[158:159], v[62:65]
	flat_store_dwordx4 v[158:159], v[58:61] offset:16
	v_add_f32_e32 v0, v138, v0
	v_pk_mul_f32 v[64:65], v[80:81], v[64:65]
	v_pk_mul_f32 v[62:63], v[78:79], v[62:63]
	v_pk_mul_f32 v[138:139], v[76:77], v[60:61]
	v_pk_mul_f32 v[60:61], v[74:75], v[58:59]
	v_cvt_pk_bf16_f32 v58, v62, v63
	v_cvt_pk_bf16_f32 v59, v64, v65
	v_pk_add_f32 v[56:57], v[136:137], v[56:57]
	v_pk_add_f32 v[54:55], v[134:135], v[54:55]
	v_cvt_pk_bf16_f32 v60, v60, v61
	v_cvt_pk_bf16_f32 v61, v138, v139
	flat_store_dwordx4 v[160:161], v[58:61]
	v_pk_add_f32 v[50:51], v[130:131], v[50:51]
	v_pk_add_f32 v[52:53], v[132:133], v[52:53]
	v_mul_f32_e32 v58, v55, v55
	v_mul_f32_e32 v59, v57, v57
	v_fmac_f32_e32 v58, v54, v54
	v_fmac_f32_e32 v59, v56, v56
	v_add_f32_e32 v58, v58, v59
	v_mul_f32_e32 v59, v51, v51
	v_fmac_f32_e32 v59, v50, v50
	v_add_f32_e32 v58, v59, v58
	v_mul_f32_e32 v59, v53, v53
	v_fmac_f32_e32 v59, v52, v52
	v_add_f32_e32 v58, v59, v58
	v_add_f32_e32 v0, v0, v58
	flat_store_dwordx4 v[158:159], v[54:57] offset:512
	flat_store_dwordx4 v[158:159], v[50:53] offset:528
	v_pk_mul_f32 v[60:61], v[66:67], v[50:51]
	v_pk_mul_f32 v[54:55], v[70:71], v[54:55]
	v_pk_mul_f32 v[56:57], v[72:73], v[56:57]
	s_nop 1
	v_mov_b32_e32 v62, v0
	s_nop 1
	v_permlane16_swap_b32_e32 v0, v62
	v_add_f32_e32 v0, v0, v62
	v_mov_b32_e32 v50, v0
	s_nop 1
	v_permlane32_swap_b32_e32 v0, v50
	v_add_f32_e32 v0, v0, v50
	v_pk_mul_f32 v[58:59], v[68:69], v[52:53]
	v_cvt_pk_bf16_f32 v52, v54, v55
	v_cvt_pk_bf16_f32 v53, v56, v57
	v_cvt_pk_bf16_f32 v54, v60, v61
	s_nop 0
	v_cvt_pk_bf16_f32 v55, v58, v59
	flat_store_dwordx4 v[160:161], v[52:55] offset:256
	s_and_saveexec_b64 s[4:5], vcc
	s_cbranch_execz .LBB0_1124
	flat_atomic_add_f32 v[194:195], v0 offset:512
.LBB0_1124:
	s_or_b64 exec, exec, s[4:5]
	v_pk_add_f32 v[48:49], v[128:129], v[48:49]
	v_pk_add_f32 v[46:47], v[126:127], v[46:47]
	v_mul_f32_e32 v52, v49, v49
	v_mul_f32_e32 v0, v47, v47
	v_pk_add_f32 v[42:43], v[122:123], v[42:43]
	v_fmac_f32_e32 v0, v46, v46
	v_fmac_f32_e32 v52, v48, v48
	v_add_f32_e32 v0, v0, v52
	v_mul_f32_e32 v52, v43, v43
	v_ashrrev_i32_e32 v157, 31, v156
	v_pk_add_f32 v[44:45], v[124:125], v[44:45]
	v_fmac_f32_e32 v52, v42, v42
	v_lshlrev_b64 v[50:51], 11, v[156:157]
	v_add_f32_e32 v0, v52, v0
	v_mul_f32_e32 v52, v45, v45
	v_lshl_add_u64 v[50:51], s[58:59], 0, v[50:51]
	v_fmac_f32_e32 v52, v44, v44
	v_lshl_add_u64 v[50:51], v[232:233], 1, v[50:51]
	flat_store_dwordx4 v[154:155], v[46:49]
	flat_store_dwordx4 v[154:155], v[42:45] offset:16
	v_add_f32_e32 v0, v52, v0
	v_pk_mul_f32 v[48:49], v[80:81], v[48:49]
	v_pk_mul_f32 v[46:47], v[78:79], v[46:47]
	v_pk_mul_f32 v[52:53], v[76:77], v[44:45]
	v_pk_mul_f32 v[44:45], v[74:75], v[42:43]
	v_cvt_pk_bf16_f32 v42, v46, v47
	v_cvt_pk_bf16_f32 v43, v48, v49
	v_pk_add_f32 v[40:41], v[120:121], v[40:41]
	v_pk_add_f32 v[38:39], v[118:119], v[38:39]
	v_cvt_pk_bf16_f32 v44, v44, v45
	v_cvt_pk_bf16_f32 v45, v52, v53
	flat_store_dwordx4 v[50:51], v[42:45]
	v_pk_add_f32 v[34:35], v[114:115], v[34:35]
	v_pk_add_f32 v[36:37], v[116:117], v[36:37]
	v_mul_f32_e32 v42, v39, v39
	v_mul_f32_e32 v43, v41, v41
	v_fmac_f32_e32 v42, v38, v38
	v_fmac_f32_e32 v43, v40, v40
	v_add_f32_e32 v42, v42, v43
	v_mul_f32_e32 v43, v35, v35
	v_fmac_f32_e32 v43, v34, v34
	v_add_f32_e32 v42, v43, v42
	v_mul_f32_e32 v43, v37, v37
	v_fmac_f32_e32 v43, v36, v36
	v_add_f32_e32 v42, v43, v42
	v_add_f32_e32 v0, v0, v42
	flat_store_dwordx4 v[154:155], v[38:41] offset:512
	flat_store_dwordx4 v[154:155], v[34:37] offset:528
	v_pk_mul_f32 v[44:45], v[66:67], v[34:35]
	v_pk_mul_f32 v[38:39], v[70:71], v[38:39]
	v_pk_mul_f32 v[40:41], v[72:73], v[40:41]
	s_nop 1
	v_mov_b32_e32 v46, v0
	s_nop 1
	v_permlane16_swap_b32_e32 v0, v46
	v_add_f32_e32 v0, v0, v46
	v_mov_b32_e32 v34, v0
	s_nop 1
	v_permlane32_swap_b32_e32 v0, v34
	v_add_f32_e32 v0, v0, v34
	v_pk_mul_f32 v[42:43], v[68:69], v[36:37]
	v_cvt_pk_bf16_f32 v36, v38, v39
	v_cvt_pk_bf16_f32 v37, v40, v41
	v_cvt_pk_bf16_f32 v38, v44, v45
	s_nop 0
	v_cvt_pk_bf16_f32 v39, v42, v43
	flat_store_dwordx4 v[50:51], v[36:39] offset:256
	s_and_saveexec_b64 s[4:5], vcc
	s_cbranch_execz .LBB0_1126
	flat_atomic_add_f32 v[194:195], v0 offset:576
; __device__ __forceinline__ float lane_xor(float v, int lane, int o) { return __builtin_bit_cast(float, __builtin_amdgcn_ds_bpermute((lane ^ o) << 2, __builtin_bit_cast(int, v))); }
; __device__ __forceinline__ unsigned cvt_pk_bf16(float lo, float hi) { unsigned r; asm volatile("v_cvt_pk_bf16_f32 %0, %1, %2" : "=v"(r) : "v"(lo), "v"(hi)); return r; }
;     __device__ __forceinline__ void operator()(const f32x4 (&acc)[2][2][4][2], const Unit& u, int wr, int wc, int fr_in, int fq_in) const {
;     ...
;             for (int m = 0; m < 4; ++m) {
;                 const int row = row0 + ai * HALF + m * 16;
;                 bf16_t* xp = XN + (size_t)row * DM + col0;
;                 float sq = 0.f;
; #pragma unroll
;                 for (int bj = 0; bj < 2; ++bj) {
;                     const f32x4 a = hv[m][bj][0] + acc[ai][bj][m][0] * alpha, b = hv[m][bj][1] + acc[ai][bj][m][1] * alpha;
;                     *(f32x4*)(hp[m] + bj * HALF) = a; *(f32x4*)(hp[m] + bj * HALF + 4) = b;
;                     sq += (a[0] * a[0] + a[1] * a[1]) + (a[2] * a[2] + a[3] * a[3]) + (b[0] * b[0] + b[1] * b[1]) + (b[2] * b[2] + b[3] * b[3]);
;                     const f32x4 xa = a * gv[bj][0], xb = b * gv[bj][1];
;                     u32x4 w; w.x = cvt_pk_bf16(xa[0], xa[1]); w.y = cvt_pk_bf16(xa[2], xa[3]); w.z = cvt_pk_bf16(xb[0], xb[1]); w.w = cvt_pk_bf16(xb[2], xb[3]);
;                     *(u32x4*)(xp + bj * HALF) = w;
;                 }
;                 sq += lane_xor(sq, lane, 16); sq += lane_xor(sq, lane, 32);
;                 if (fq == 0) atomicAdd(SSout + row, sq);
.LBB0_1126:
	s_or_b64 exec, exec, s[4:5]
	v_pk_add_f32 v[32:33], v[112:113], v[32:33]
	v_pk_add_f32 v[30:31], v[110:111], v[30:31]
	v_mul_f32_e32 v36, v33, v33
	v_mul_f32_e32 v0, v31, v31
	v_pk_add_f32 v[26:27], v[106:107], v[26:27]
	v_fmac_f32_e32 v0, v30, v30
	v_fmac_f32_e32 v36, v32, v32
	v_add_f32_e32 v0, v0, v36
	v_mul_f32_e32 v36, v27, v27
	v_ashrrev_i32_e32 v153, 31, v152
	v_pk_add_f32 v[28:29], v[108:109], v[28:29]
	v_fmac_f32_e32 v36, v26, v26
	v_lshlrev_b64 v[34:35], 11, v[152:153]
	v_add_f32_e32 v0, v36, v0
	v_mul_f32_e32 v36, v29, v29
	v_lshl_add_u64 v[34:35], s[58:59], 0, v[34:35]
	v_fmac_f32_e32 v36, v28, v28
	v_lshl_add_u64 v[34:35], v[232:233], 1, v[34:35]
	flat_store_dwordx4 v[150:151], v[30:33]
	flat_store_dwordx4 v[150:151], v[26:29] offset:16
	v_add_f32_e32 v0, v36, v0
	v_pk_mul_f32 v[32:33], v[80:81], v[32:33]
	v_pk_mul_f32 v[30:31], v[78:79], v[30:31]
	v_pk_mul_f32 v[36:37], v[76:77], v[28:29]
	v_pk_mul_f32 v[28:29], v[74:75], v[26:27]
	v_cvt_pk_bf16_f32 v26, v30, v31
	v_cvt_pk_bf16_f32 v27, v32, v33
	v_pk_add_f32 v[24:25], v[104:105], v[24:25]
	v_pk_add_f32 v[22:23], v[102:103], v[22:23]
	v_cvt_pk_bf16_f32 v28, v28, v29
	v_cvt_pk_bf16_f32 v29, v36, v37
	flat_store_dwordx4 v[34:35], v[26:29]
	v_pk_add_f32 v[18:19], v[98:99], v[18:19]
	v_pk_add_f32 v[20:21], v[100:101], v[20:21]
	v_mul_f32_e32 v26, v23, v23
	v_mul_f32_e32 v27, v25, v25
	v_fmac_f32_e32 v26, v22, v22
	v_fmac_f32_e32 v27, v24, v24
	v_add_f32_e32 v26, v26, v27
	v_mul_f32_e32 v27, v19, v19
	v_fmac_f32_e32 v27, v18, v18
	v_add_f32_e32 v26, v27, v26
	v_mul_f32_e32 v27, v21, v21
	v_fmac_f32_e32 v27, v20, v20
	v_add_f32_e32 v26, v27, v26
	v_add_f32_e32 v0, v0, v26
	flat_store_dwordx4 v[150:151], v[22:25] offset:512
	flat_store_dwordx4 v[150:151], v[18:21] offset:528
	v_pk_mul_f32 v[28:29], v[66:67], v[18:19]
	v_pk_mul_f32 v[22:23], v[70:71], v[22:23]
	v_pk_mul_f32 v[24:25], v[72:73], v[24:25]
	s_nop 1
	v_mov_b32_e32 v30, v0
	s_nop 1
	v_permlane16_swap_b32_e32 v0, v30
	v_add_f32_e32 v0, v0, v30
	v_mov_b32_e32 v18, v0
	s_nop 1
	v_permlane32_swap_b32_e32 v0, v18
	v_add_f32_e32 v0, v0, v18
	v_pk_mul_f32 v[26:27], v[68:69], v[20:21]
	v_cvt_pk_bf16_f32 v20, v22, v23
	v_cvt_pk_bf16_f32 v21, v24, v25
	v_cvt_pk_bf16_f32 v22, v28, v29
	s_nop 0
	v_cvt_pk_bf16_f32 v23, v26, v27
	flat_store_dwordx4 v[34:35], v[20:23] offset:256
	s_and_saveexec_b64 s[4:5], vcc
	s_cbranch_execz .LBB0_1128
	flat_atomic_add_f32 v[194:195], v0 offset:640
.LBB0_1128:
	s_or_b64 exec, exec, s[4:5]
	v_pk_add_f32 v[16:17], v[96:97], v[16:17]
	v_pk_add_f32 v[14:15], v[94:95], v[14:15]
	v_mul_f32_e32 v20, v17, v17
	v_mul_f32_e32 v0, v15, v15
	v_pk_add_f32 v[10:11], v[90:91], v[10:11]
	v_fmac_f32_e32 v0, v14, v14
	v_fmac_f32_e32 v20, v16, v16
	v_add_f32_e32 v0, v0, v20
	v_mul_f32_e32 v20, v11, v11
	v_ashrrev_i32_e32 v149, 31, v148
	v_pk_add_f32 v[12:13], v[92:93], v[12:13]
	v_fmac_f32_e32 v20, v10, v10
	v_lshlrev_b64 v[18:19], 11, v[148:149]
	v_add_f32_e32 v0, v20, v0
	v_mul_f32_e32 v20, v13, v13
	v_lshl_add_u64 v[18:19], s[58:59], 0, v[18:19]
	v_fmac_f32_e32 v20, v12, v12
	v_lshl_add_u64 v[18:19], v[232:233], 1, v[18:19]
	flat_store_dwordx4 v[146:147], v[14:17]
	flat_store_dwordx4 v[146:147], v[10:13] offset:16
	v_add_f32_e32 v0, v20, v0
	v_pk_mul_f32 v[16:17], v[80:81], v[16:17]
	v_pk_mul_f32 v[14:15], v[78:79], v[14:15]
	v_pk_mul_f32 v[20:21], v[76:77], v[12:13]
	v_pk_mul_f32 v[12:13], v[74:75], v[10:11]
	v_cvt_pk_bf16_f32 v10, v14, v15
	v_cvt_pk_bf16_f32 v11, v16, v17
	v_pk_add_f32 v[8:9], v[88:89], v[8:9]
	v_pk_add_f32 v[6:7], v[86:87], v[6:7]
	v_cvt_pk_bf16_f32 v12, v12, v13
	v_cvt_pk_bf16_f32 v13, v20, v21
	flat_store_dwordx4 v[18:19], v[10:13]
	v_pk_add_f32 v[2:3], v[82:83], v[2:3]
	v_pk_add_f32 v[4:5], v[84:85], v[4:5]
	v_mul_f32_e32 v10, v7, v7
	v_mul_f32_e32 v11, v9, v9
	v_fmac_f32_e32 v10, v6, v6
	v_fmac_f32_e32 v11, v8, v8
	v_add_f32_e32 v10, v10, v11
	v_mul_f32_e32 v11, v3, v3
	v_fmac_f32_e32 v11, v2, v2
	v_add_f32_e32 v10, v11, v10
	v_mul_f32_e32 v11, v5, v5
	v_fmac_f32_e32 v11, v4, v4
	v_add_f32_e32 v10, v11, v10
	v_add_f32_e32 v0, v0, v10
	flat_store_dwordx4 v[146:147], v[6:9] offset:512
	flat_store_dwordx4 v[146:147], v[2:5] offset:528
	v_pk_mul_f32 v[12:13], v[66:67], v[2:3]
	v_pk_mul_f32 v[6:7], v[70:71], v[6:7]
	v_pk_mul_f32 v[8:9], v[72:73], v[8:9]
	s_nop 1
	v_mov_b32_e32 v14, v0
	s_nop 1
	v_permlane16_swap_b32_e32 v0, v14
	v_add_f32_e32 v0, v0, v14
	v_mov_b32_e32 v2, v0
	s_nop 1
	v_permlane32_swap_b32_e32 v0, v2
	v_add_f32_e32 v0, v0, v2
	v_pk_mul_f32 v[10:11], v[68:69], v[4:5]
	v_cvt_pk_bf16_f32 v4, v6, v7
	v_cvt_pk_bf16_f32 v5, v8, v9
	v_cvt_pk_bf16_f32 v6, v12, v13
	s_nop 0
	v_cvt_pk_bf16_f32 v7, v10, v11
	flat_store_dwordx4 v[18:19], v[4:7] offset:256
	s_and_saveexec_b64 s[4:5], vcc
	s_cbranch_execz .LBB0_1130
	flat_atomic_add_f32 v[194:195], v0 offset:704
